# c14 with the bv stores ordered so that the two 256-byte pieces of a 512-byte run are consecutive instructions
# speedup vs baseline: 1.0084x; 1.0084x over previous
;     __device__ __forceinline__ void operator()(const f32x4 (&acc)[2][2][4][2], const pg8::Unit& u, int wr, int wc, int fr, int fq) const {
;     ...
;                         const int dvg = colt + bj * 128 + wc * 32 + col;
;                         if (isb) { const size_t gc = (size_t)u.pm * 4 + ai * 2 + wr;
;                             *(u32x4*)(VO + ((((gc * 4 + (dvg >> 9)) * 16 + ((dvg >> 5) & 15)) * 4 + m) * 64 + half * 32 + col) * 8) = w; }
.Lp2_bv:
	s_lshl_b32 s3, s12, 20
	s_and_b32 s7, s0, 3
	s_lshl_b32 s7, s7, 18
	s_add_u32 s3, s3, s7
	s_sub_i32 s7, s6, 24
	s_and_b32 s7, s7, 7
	s_lshr_b32 s32, s7, 1
	s_lshl_b32 s32, s32, 16
	s_add_u32 s3, s3, s32
	s_and_b32 s7, s7, 1
	s_lshl_b32 s7, s7, 15
	s_add_u32 s3, s3, s7
	s_bfe_u32 s7, s0, 0x10002
	s_lshl_b32 s7, s7, 13
	s_add_u32 s3, s3, s7
	s_add_u32 s40, s40, s3
	s_addc_u32 s41, s41, 0
	v_lshrrev_b32_e32 v68, 4, v160
	v_and_b32_e32 v74, 15, v160
	v_lshlrev_b32_e32 v68, 9, v68
	v_lshl_or_b32 v68, v74, 4, v68
	v_mov_b32_e32 v69, 0
	v_lshl_add_u64 v[68:69], s[40:41], 0, v[68:69]
	s_mov_b64 s[56:57], 0x1000
	v_lshl_add_u64 v[246:247], v[68:69], 0, s[56:57]
	s_mov_b64 s[56:57], 0x4000
	v_lshl_add_u64 v[248:249], v[68:69], 0, s[56:57]
	s_mov_b64 s[56:57], 0x5000
	v_lshl_add_u64 v[250:251], v[68:69], 0, s[56:57]
	global_store_dwordx4 v[68:69], v[130:133], off nt
	global_store_dwordx4 v[68:69], v[122:125], off offset:256 nt
	global_store_dwordx4 v[68:69], v[126:129], off offset:2048 nt
	global_store_dwordx4 v[68:69], v[118:121], off offset:2304 nt
	global_store_dwordx4 v[246:247], v[114:117], off nt
	global_store_dwordx4 v[246:247], v[106:109], off offset:256 nt
	global_store_dwordx4 v[246:247], v[110:113], off offset:2048 nt
	global_store_dwordx4 v[246:247], v[102:105], off offset:2304 nt
	global_store_dwordx4 v[248:249], v[98:101], off nt
	global_store_dwordx4 v[248:249], v[90:93], off offset:256 nt
	global_store_dwordx4 v[248:249], v[94:97], off offset:2048 nt
	global_store_dwordx4 v[248:249], v[86:89], off offset:2304 nt
	global_store_dwordx4 v[250:251], v[82:85], off nt
	global_store_dwordx4 v[250:251], v[70:73], off offset:256 nt
	global_store_dwordx4 v[250:251], v[78:81], off offset:2048 nt
	global_store_dwordx4 v[250:251], v[64:67], off offset:2304 nt
	s_mov_b64 s[44:45], 0
